# fused-LN row-statistics exchange without the L1 invalidate (slots are read by sc1 loads only); redundant vmcnt(0) after the attention prologue barrier removed
# speedup vs baseline: 1.0970x; 1.0076x over previous
.LBB0_759:
	s_nop 0
	v_lshlrev_b32_e32 v12, 16, v14
	s_and_b32 s30, s57, 0x3fffffc0
	v_lshlrev_b32_e32 v10, 16, v18
	v_pk_mul_f32 v[12:13], v[4:5], v[12:13] op_sel:[1,0] op_sel_hi:[0,0]
	s_lshl_b32 s30, s30, 2
	v_pk_fma_f32 v[30:31], v[4:5], v[10:11], v[12:13] neg_lo:[0,0,1] neg_hi:[0,0,1]
	v_pk_fma_f32 v[4:5], v[4:5], v[10:11], v[12:13] op_sel_hi:[1,0,1]
	v_and_b32_e32 v10, 0xffff0000, v14
	s_add_i32 s30, s30, 0
	v_and_b32_e32 v4, 0xffff0000, v18
	v_pk_mul_f32 v[10:11], v[6:7], v[10:11] op_sel:[1,0] op_sel_hi:[0,0]
	v_mov_b32_e32 v9, v137
	s_add_i32 s30, s30, 0x14000
	v_cvt_pk_bf16_f32 v38, v30, v5
	v_pk_fma_f32 v[12:13], v[6:7], v[4:5], v[10:11] neg_lo:[0,0,1] neg_hi:[0,0,1]
	v_pk_fma_f32 v[4:5], v[6:7], v[4:5], v[10:11] op_sel_hi:[1,0,1]
	v_lshlrev_b32_e32 v6, 16, v15
	v_lshl_add_u64 v[154:155], s[6:7], 0, v[8:9]
	s_or_b32 s6, s34, 0x10000
	v_lshlrev_b32_e32 v4, 16, v19
	v_pk_mul_f32 v[6:7], v[0:1], v[6:7] op_sel:[1,0] op_sel_hi:[0,0]
	s_mov_b32 s7, s11
	s_cmp_lg_u32 0, -1
	v_cvt_pk_bf16_f32 v39, v12, v5
	v_pk_fma_f32 v[10:11], v[0:1], v[4:5], v[6:7] neg_lo:[0,0,1] neg_hi:[0,0,1]
	v_pk_fma_f32 v[0:1], v[0:1], v[4:5], v[6:7] op_sel_hi:[1,0,1]
	v_lshl_add_u64 v[4:5], v[154:155], 0, s[6:7]
	s_cselect_b32 s6, 0, 0
	s_add_i32 s6, s6, s55
	s_add_i32 s6, s6, 0x10000
	s_mov_b32 s7, m0
	s_mov_b32 m0, s6
	s_nop 0
	global_load_lds_dwordx4 v[4:5], off
	s_mov_b32 m0, s7
	ds_read_b128 v[4:7], v151
	ds_read_b128 v[30:33], v151 offset:2048
	v_cvt_pk_bf16_f32 v40, v10, v1
	v_and_b32_e32 v10, 0xffff0000, v15
	v_and_b32_e32 v0, 0xffff0000, v19
	v_pk_mul_f32 v[8:9], v[2:3], v[10:11] op_sel:[1,0] op_sel_hi:[0,0]
	v_pk_fma_f32 v[10:11], v[2:3], v[0:1], v[8:9] neg_lo:[0,0,1] neg_hi:[0,0,1]
	v_pk_fma_f32 v[0:1], v[2:3], v[0:1], v[8:9] op_sel_hi:[1,0,1]
	v_lshlrev_b32_e32 v34, 16, v16
	v_cvt_pk_bf16_f32 v41, v10, v1
	s_waitcnt lgkmcnt(1)
	v_mfma_f32_32x32x16_bf16 v[0:15], v[4:7], v[92:95], 0
	v_lshlrev_b32_e32 v18, 16, v20
	v_pk_mul_f32 v[34:35], v[26:27], v[34:35] op_sel:[1,0] op_sel_hi:[0,0]
	v_pk_fma_f32 v[36:37], v[26:27], v[18:19], v[34:35] neg_lo:[0,0,1] neg_hi:[0,0,1]
	v_pk_fma_f32 v[18:19], v[26:27], v[18:19], v[34:35] op_sel_hi:[1,0,1]
	v_and_b32_e32 v16, 0xffff0000, v16
	v_cvt_pk_bf16_f32 v42, v36, v19
	ds_read_b128 v[34:37], v151 offset:4096
	s_waitcnt lgkmcnt(1)
	v_mfma_f32_32x32x16_bf16 v[0:15], v[30:33], v[88:91], v[0:15]
	v_and_b32_e32 v18, 0xffff0000, v20
	v_mul_f32_e64 v26, v29, v16
	v_mul_f32_e64 v27, v28, v16
	v_fma_f32 v30, v28, v18, -v26
	v_fma_f32 v31, v29, v19, -v27
	v_pk_fma_f32 v[18:19], v[28:29], v[18:19], v[26:27] op_sel_hi:[1,0,1]
	ds_read_b128 v[26:29], v151 offset:6144
	v_lshlrev_b32_e32 v18, 16, v17
	v_cvt_pk_bf16_f32 v32, v30, v19
	s_waitcnt lgkmcnt(1)
	v_mfma_f32_32x32x16_bf16 v[0:15], v[34:37], v[84:87], v[0:15]
	v_lshlrev_b32_e32 v16, 16, v21
	v_pk_mul_f32 v[18:19], v[22:23], v[18:19] op_sel:[1,0] op_sel_hi:[0,0]
	v_pk_fma_f32 v[30:31], v[22:23], v[16:17], v[18:19] neg_lo:[0,0,1] neg_hi:[0,0,1]
	v_pk_fma_f32 v[18:19], v[22:23], v[16:17], v[18:19] op_sel_hi:[1,0,1]
	v_and_b32_e32 v16, 0xffff0000, v21
	v_cvt_pk_bf16_f32 v30, v30, v19
	ds_read_b128 v[18:21], v151 offset:8192
	s_waitcnt lgkmcnt(1)
	v_mfma_f32_32x32x16_bf16 v[0:15], v[26:29], v[80:83], v[0:15]
	v_and_b32_e32 v22, 0xffff0000, v17
	v_pk_mul_f32 v[22:23], v[24:25], v[22:23] op_sel:[1,0] op_sel_hi:[0,0]
	v_pk_fma_f32 v[26:27], v[24:25], v[16:17], v[22:23] neg_lo:[0,0,1] neg_hi:[0,0,1]
	v_pk_fma_f32 v[16:17], v[24:25], v[16:17], v[22:23] op_sel_hi:[1,0,1]
	v_perm_b32 v96, v39, v38, s48
	v_cvt_pk_bf16_f32 v16, v26, v17
	v_perm_b32 v97, v41, v40, s48
	v_perm_b32 v98, v32, v42, s48
	v_perm_b32 v99, v16, v30, s48
	ds_read_b128 v[22:25], v151 offset:10240
	v_perm_b32 v101, v41, v40, s49
	s_waitcnt lgkmcnt(1)
	v_mfma_f32_32x32x16_bf16 v[0:15], v[18:21], v[96:99], v[0:15]
	ds_read_b64_tr_b16 v[40:41],v161 offset:0
	v_perm_b32 v102, v32, v42, s49
	ds_read_b64_tr_b16 v[42:43],v161 offset:512
	ds_read_b64_tr_b16 v[44:45],v161 offset:1024
	ds_read_b64_tr_b16 v[46:47],v161 offset:1536
	ds_read_b64_tr_b16 v[68:69],v161 offset:2048
	ds_read_b64_tr_b16 v[70:71],v161 offset:2560
	ds_read_b64_tr_b16 v[64:65],v161 offset:3072
	v_perm_b32 v100, v39, v38, s49
	v_perm_b32 v103, v16, v30, s49
	ds_read_b64_tr_b16 v[66:67],v161 offset:3584
	ds_read_b64_tr_b16 v[60:61],v161 offset:4096
	ds_read_b64_tr_b16 v[62:63],v161 offset:4608
	ds_read_b64_tr_b16 v[56:57],v161 offset:5120
	ds_read_b64_tr_b16 v[58:59],v161 offset:5632
	s_waitcnt lgkmcnt(0)
	s_nop 0
	v_mfma_f32_32x32x16_bf16 v[0:15], v[22:25], v[100:103], v[0:15]
	v_max3_f32 v8, v0, v1, v168
	v_max3_f32 v9, v2, v3, v168
	ds_read_b64_tr_b16 v[52:53],v161 offset:6144
	ds_read_b64_tr_b16 v[54:55],v161 offset:6656
	ds_read_b64_tr_b16 v[48:49],v161 offset:7168
	ds_read_b64_tr_b16 v[50:51],v161 offset:7680
	s_nop 0
	v_max3_f32 v8, v8, v168, v168
	v_max3_f32 v9, v9, v6, v7
	v_lshl_add_u32 v171, v143, 2, s30
	v_max3_f32 v8, v8, v4, v5
	v_max3_f32 v9, v9, v168, v168
	s_nop 0
	v_max3_f32 v8, v8, v168, v168
	v_max3_f32 v9, v9, v168, v168
	s_nop 0
	v_max3_f32 v8, v8, v168, v168
	v_max3_f32 v9, v9, v168, v168
	s_nop 0
	v_max3_f32 v8, v8, v168, v168
	v_max3_f32 v9, v9, v168, v168
	s_nop 0
	v_max3_f32 v8, v8, v168, v168
	v_max3_f32 v9, v9, v168, v168
	s_nop 0
	v_max3_f32 v8, v8, v168, v168
	s_nop 0
	v_max_f32_e32 v8, v8, v9
	s_nop 3
	v_mov_b32_e32 v9, v8
	s_nop 1
	v_permlane32_swap_b32_e32 v8, v9
	v_max_f32_e32 v174, v8, v9
	s_and_saveexec_b64 s[6:7], s[0:1]
	ds_write_b32 v171, v137
	s_or_b64 exec, exec, s[6:7]
	s_waitcnt lgkmcnt(0)
	v_add_u32_e32 v172, s30, v162
	v_sub_f32_e32 v24, v0, v174
	v_sub_f32_e32 v26, v1, v174
	v_sub_f32_e32 v27, v2, v174
	v_sub_f32_e32 v28, v3, v174
	v_sub_f32_e32 v29, v4, v174
	v_sub_f32_e32 v30, v5, v174
	v_sub_f32_e32 v31, v6, v174
	v_sub_f32_e32 v39, v7, v174
	ds_read_b128 v[0:3], v172 offset:64
	ds_read_b128 v[4:7], v172 offset:96
	ds_read_b128 v[16:19], v172
	ds_read_b128 v[20:23], v172 offset:32
	v_sub_f32_e32 v25, 0xf149f2ca, v174
	s_waitcnt lgkmcnt(3)
	v_pk_mul_f32 v[8:9], v[0:1], 0 op_sel_hi:[1,0]
	v_exp_f32_e32 v104, v25
	s_waitcnt lgkmcnt(1)
	v_pk_mul_f32 v[0:1], v[16:17], 0 op_sel_hi:[1,0]
	v_exp_f32_e32 v17, v30
	v_exp_f32_e32 v16, v31
	v_exp_f32_e32 v108, v24
	v_exp_f32_e32 v109, v26
	v_exp_f32_e32 v110, v27
	v_exp_f32_e32 v111, v28
	v_exp_f32_e32 v112, v29
	v_pk_add_f32 v[106:107], v[16:17], v[104:105] op_sel_hi:[1,0]
	v_exp_f32_e32 v105, v39
	v_cvt_pk_bf16_f32 v72, v108, v109
	v_cvt_pk_bf16_f32 v73, v110, v111
	v_cvt_pk_bf16_f32 v74, v112, v17
	v_cvt_pk_bf16_f32 v75, v16, v105
	v_pk_mul_f32 v[14:15], v[6:7], 0 op_sel_hi:[1,0]
	v_pk_mul_f32 v[10:11], v[2:3], 0 op_sel_hi:[1,0]
	s_waitcnt lgkmcnt(0)
	v_pk_mul_f32 v[6:7], v[22:23], 0 op_sel_hi:[1,0]
	v_pk_mul_f32 v[2:3], v[18:19], 0 op_sel_hi:[1,0]
	v_pk_mul_f32 v[12:13], v[4:5], 0 op_sel_hi:[1,0]
	v_pk_mul_f32 v[4:5], v[20:21], 0 op_sel_hi:[1,0]
	s_waitcnt lgkmcnt(0)
	v_cvt_pk_bf16_f32 v76, v104, v104
	v_mov_b32_e32 v77, v76
	v_mfma_f32_32x32x16_bf16 v[16:31], v[72:75], v[40:43], v[0:15]
	v_mov_b32_e32 v78, v76
	v_mov_b32_e32 v79, v76
	s_lshl_b32 s30, s36, 2
	s_or_b32 s31, s30, 2
	s_lshr_b32 s6, s57, 7
	s_lshl_b32 s54, s37, 6
	s_add_i32 s57, s31, s6
	v_mfma_f32_32x32x16_bf16 v[16:31], v[76:79], v[44:47], v[16:31]
	s_add_i32 s59, s55, 0x2000
	s_cmp_lg_u32 0, -1
	s_cselect_b32 s6, 0, 0
	s_add_i32 s58, s6, s55
	s_bfe_u32 s34, s44, 0x3000c
	s_lshl_b32 s6, s44, 10
	s_and_b32 s6, s6, 0x1c00000
	v_mfma_f32_32x32x16_bf16 v[0:15], v[72:75], v[60:63], v[0:15]
	v_add_f32_e32 v61, v109, v104
	s_mov_b32 s7, s11
	s_mul_i32 s34, s34, 0x600000
	s_mulk_i32 s37, 0xc0
	s_add_i32 s58, s58, 0xc000
	v_xor_b32_e32 v32, 0x80000000, v174
	v_mov_b32_e32 v33, v32
	v_mfma_f32_32x32x16_bf16 v[16:31], v[76:79], v[68:71], v[16:31]
	v_mov_b32_e32 v34, v32
	v_mov_b32_e32 v35, v32
	v_mov_b32_e32 v36, v32
	v_mov_b32_e32 v37, v32
	v_mov_b32_e32 v38, v32
	v_mov_b32_e32 v39, v32
	v_mov_b32_e32 v40, v32
	v_mfma_f32_32x32x16_bf16 v[0:15], v[76:79], v[56:59], v[0:15]
	v_add_f32_e32 v56, v112, v104
	v_mov_b32_e32 v41, v32
	v_mov_b32_e32 v42, v32
	v_mov_b32_e32 v43, v32
	v_mov_b32_e32 v44, v32
	v_mov_b32_e32 v45, v32
	v_mov_b32_e32 v46, v32
	v_mfma_f32_32x32x16_bf16 v[16:31], v[76:79], v[64:67], v[16:31]
	v_add_f32_e32 v64, v108, v104
	v_add_f32_e32 v60, 0, v64
	v_add_f32_e32 v60, v61, v60
	v_add_f32_e32 v61, v110, v104
	v_add_f32_e32 v60, v61, v60
	v_add_f32_e32 v61, v111, v104
	v_add_f32_e32 v60, v61, v60
	v_mfma_f32_32x32x16_bf16 v[0:15], v[76:79], v[52:55], v[0:15]
	v_add_f32_e32 v56, v56, v60
	v_add_f32_e32 v56, v107, v56
	v_add_f32_e32 v58, v106, v56
	v_add_f32_e64 v56, v104, v104
	v_add_f32_e64 v57, v105, v104
	v_mov_b32_e32 v47, v32
	v_add_f32_e32 v57, v57, v58
	v_add_f32_e32 v57, v56, v57
	v_add_f32_e32 v52, v56, v57
	v_mfma_f32_32x32x16_bf16 v[0:15], v[76:79], v[48:51], v[0:15]
	v_add_f32_e32 v52, v56, v52
	v_add_f32_e32 v52, v56, v52
	v_add_f32_e32 v52, v56, v52
	v_add_f32_e32 v52, v56, v52
	v_lshl_add_u64 v[48:49], v[154:155], 0, s[6:7]
	s_or_b32 s6, s34, s37
	v_add_f32_e32 v52, v56, v52
	s_add_u32 s6, s46, s6
	v_add_f32_e32 v52, v56, v52
	s_addc_u32 s7, s47, 0
	v_add_f32_e32 v173, 0, v52
	v_lshl_add_u64 v[156:157], v[48:49], 0, s[22:23]
	v_lshl_add_u64 v[158:159], s[6:7], 0, v[136:137]
	s_mov_b32 s60, -2
	s_branch .LBB0_765

.LBB0_1017:
	s_andn2_b64 vcc, exec, s[34:35]
	s_cbranch_vccz .LBB0_1023
	s_waitcnt lgkmcnt(0)
	s_and_saveexec_b64 s[28:29], s[8:9]
	s_xor_b64 s[28:29], exec, s[28:29]
	s_cbranch_execz .LBB0_1020
	s_nop 0

.LBB0_1024:
	s_waitcnt vmcnt(0)
	s_nop 0
	s_and_b64 exec, exec, s[6:7]
	v_cndmask_b32_e64 v133, 0, 1, s[10:11]
	ds_write_b32 v171, v133 offset:10240

.LBB0_1312:
	s_andn2_b64 vcc, exec, s[28:29]
	s_cbranch_vccz .LBB0_1318
	s_waitcnt lgkmcnt(0)
	s_and_saveexec_b64 s[8:9], s[6:7]
	s_xor_b64 s[8:9], exec, s[8:9]
	s_cbranch_execz .LBB0_1315
	s_nop 0

.LBB0_1319:
	s_waitcnt vmcnt(0)
	s_nop 0
	s_and_b64 exec, exec, s[4:5]
	v_cndmask_b32_e64 v133, 0, 1, s[26:27]
	ds_write_b32 v161, v133 offset:10240
